# P0 rms loop double-buffered (next row loads issued before current row compute) + compute-dtype comment
# speedup vs baseline: 1.0053x; 1.0053x over previous
; __device__ __forceinline__ unsigned pk2(float lo, float hi) { f32x2_t v = {lo, hi}; bf16x2_t b = __builtin_convertvector(v, bf16x2_t); return __builtin_bit_cast(unsigned, b); }
; __device__ __forceinline__ void rms_row2048(const float* xrow, const float* g, bf16_t* orow, int lane) {
;     const f32x4* xr = (const f32x4*)xrow + lane; const f32x4* gr = (const f32x4*)g + lane;
;     f32x4 v[8]; float s = 0.f;
; #pragma unroll
;     for (int j = 0; j < 8; ++j) { v[j] = xr[64 * j]; s += (v[j].x * v[j].x + v[j].y * v[j].y) + (v[j].z * v[j].z + v[j].w * v[j].w); }
;     const float r = rsqrtf(wave_sum(s) * (1.f / 2048.f) + EPS);
;     u32x2* o8 = (u32x2*)orow + lane;
; #pragma unroll
;     for (int j = 0; j < 8; ++j) { const f32x4 gg = gr[64 * j]; u32x2 w; w.x = pk2(v[j].x * r * gg.x, v[j].y * r * gg.y); w.y = pk2(v[j].z * r * gg.z, v[j].w * r * gg.w); o8[64 * j] = w; }
; __global__ void __launch_bounds__(512, 2) mega_fwd(Args args) {
;     ...
;         for (int m = gw; m < T; m += NGW) rms_row2048(x + (size_t)m * D, args.in[3], H + (size_t)m * D, lane);
.LBB0_257:
	s_or_b64 exec, exec, s[2:3]
	v_readlane_b32 s0, v238, 38
	s_cmpk_gt_i32 s0, 0x3fff
	v_readlane_b32 s1, v238, 39
	s_cbranch_scc1 .LBB0_260
	v_lshlrev_b32_e32 v0, 4, v184
	v_mov_b32_e32 v1, 0
	v_lshl_add_u64 v[16:17], s[58:59], 0, v[0:1]
	s_mov_b64 s[0:1], 0x1000
	v_lshl_add_u64 v[18:19], v[16:17], 0, s[0:1]
	s_mov_b64 s[0:1], 0x1400
	v_lshl_add_u64 v[20:21], v[16:17], 0, s[0:1]
	s_mov_b64 s[0:1], 0x1800
	v_lshl_add_u64 v[22:23], v[16:17], 0, s[0:1]
	v_readlane_b32 s0, v238, 38
	v_readlane_b32 s1, v238, 39
	s_mov_b32 s8, s0
	s_ashr_i32 s9, s0, 31
	s_lshl_b64 s[0:1], s[8:9], 12
	s_add_u32 s0, s86, s0
	v_lshlrev_b32_e32 v2, 3, v184
	v_mov_b32_e32 v3, v1
	s_addc_u32 s1, s87, s1
	v_lshl_add_u64 v[2:3], s[0:1], 0, v[2:3]
	s_mov_b64 s[0:1], 0x6800e00
	s_ashr_i32 s97, s96, 31
	v_lshl_add_u64 v[26:27], v[2:3], 0, s[0:1]
	s_lshl_b64 s[0:1], s[96:97], 12
	s_lshl_b64 s[4:5], s[8:9], 13
	s_add_u32 s4, s52, s4
	s_addc_u32 s5, s53, s5
	s_mov_b64 s[2:3], 0x1c00
	v_lshl_add_u64 v[0:1], s[4:5], 0, v[0:1]
	s_mov_b32 s6, s8
	v_lshl_add_u64 v[24:25], v[16:17], 0, s[2:3]
	v_lshl_add_u64 v[28:29], v[0:1], 0, s[2:3]
	s_lshl_b64 s[2:3], s[96:97], 13
	v_mov_b32_e32 v30, 0x358637bd
	s_mov_b32 s4, 0x800000
	v_writelane_b32 v238, s6, 38
	s_mov_b32 s5, s8
	s_nop 0
	v_writelane_b32 v238, s7, 39
	global_load_dwordx4 v[80:83], v[16:17], off
	global_load_dwordx4 v[84:87], v[16:17], off offset:1024
	global_load_dwordx4 v[88:91], v[16:17], off offset:2048
	global_load_dwordx4 v[92:95], v[16:17], off offset:3072
	global_load_dwordx4 v[96:99], v[18:19], off
	global_load_dwordx4 v[100:103], v[20:21], off
	global_load_dwordx4 v[104:107], v[22:23], off
	global_load_dwordx4 v[108:111], v[24:25], off
	v_add_co_u32_e32 v144, vcc, 0xfffff000, v28
	global_load_dwordx4 v[112:115], v[28:29], off offset:-3072
	global_load_dwordx4 v[116:119], v[28:29], off offset:-2048
	global_load_dwordx4 v[120:123], v[28:29], off offset:-1024
	v_addc_co_u32_e32 v145, vcc, -1, v29, vcc
	global_load_dwordx4 v[124:127], v[144:145], off offset:-3072
	global_load_dwordx4 v[128:131], v[144:145], off offset:-2048
	global_load_dwordx4 v[132:135], v[144:145], off offset:-1024
	global_load_dwordx4 v[136:139], v[28:29], off offset:-4096
	s_nop 0
	global_load_dwordx4 v[140:143], v[28:29], off
	s_add_i32 s5, s5, s96
	s_cmpk_lt_i32 s5, 0x4000
	v_lshl_add_u64 v[28:29], v[28:29], 0, s[2:3]
	s_cselect_b32 s16, 1, 0
	s_waitcnt vmcnt(0)
.LBB0_259:
	v_mov_b32_e32 v4, v112
	v_mov_b32_e32 v5, v113
	v_mov_b32_e32 v6, v114
	v_mov_b32_e32 v7, v115
	v_mov_b32_e32 v12, v116
	v_mov_b32_e32 v13, v117
	v_mov_b32_e32 v14, v118
	v_mov_b32_e32 v15, v119
	v_mov_b32_e32 v8, v120
	v_mov_b32_e32 v9, v121
	v_mov_b32_e32 v10, v122
	v_mov_b32_e32 v11, v123
	v_mov_b32_e32 v32, v124
	v_mov_b32_e32 v33, v125
	v_mov_b32_e32 v34, v126
	v_mov_b32_e32 v35, v127
	v_mov_b32_e32 v36, v128
	v_mov_b32_e32 v37, v129
	v_mov_b32_e32 v38, v130
	v_mov_b32_e32 v39, v131
	v_mov_b32_e32 v40, v132
	v_mov_b32_e32 v41, v133
	v_mov_b32_e32 v42, v134
	v_mov_b32_e32 v43, v135
	v_mov_b32_e32 v44, v136
	v_mov_b32_e32 v45, v137
	v_mov_b32_e32 v46, v138
	v_mov_b32_e32 v47, v139
	v_mov_b32_e32 v0, v140
	v_mov_b32_e32 v1, v141
	v_mov_b32_e32 v2, v142
	v_mov_b32_e32 v3, v143
	s_mov_b32 s17, 0
	s_cmp_lg_u32 s16, 0
	s_cbranch_scc0 .Lp0r_nopref
	v_add_co_u32_e32 v144, vcc, 0xfffff000, v28
	global_load_dwordx4 v[112:115], v[28:29], off offset:-3072
	global_load_dwordx4 v[116:119], v[28:29], off offset:-2048
	global_load_dwordx4 v[120:123], v[28:29], off offset:-1024
	v_addc_co_u32_e32 v145, vcc, -1, v29, vcc
	global_load_dwordx4 v[124:127], v[144:145], off offset:-3072
	global_load_dwordx4 v[128:131], v[144:145], off offset:-2048
	global_load_dwordx4 v[132:135], v[144:145], off offset:-1024
	global_load_dwordx4 v[136:139], v[28:29], off offset:-4096
	s_nop 0
	global_load_dwordx4 v[140:143], v[28:29], off
	s_add_i32 s5, s5, s96
	s_cmpk_lt_i32 s5, 0x4000
	v_lshl_add_u64 v[28:29], v[28:29], 0, s[2:3]
	s_cselect_b32 s16, 1, 0
	s_mov_b32 s17, 1
.Lp0r_nopref:
	v_mov_b32_e32 v68, v35
	v_pk_mul_f32 v[52:53], v[14:15], v[14:15]
	v_pk_mul_f32 v[54:55], v[12:13], v[12:13]
	v_mul_f32_e32 v56, v9, v9
	v_mul_f32_e32 v58, v11, v11
	v_mul_f32_e32 v64, v2, v2
	v_mul_f32_e32 v65, v3, v3
	v_pk_mov_b32 v[60:61], v[54:55], v[52:53] op_sel:[1,0]
	v_mov_b32_e32 v55, v53
	v_pk_fma_f32 v[52:53], v[8:9], v[8:9], v[56:57] op_sel_hi:[1,1,0]
	v_pk_fma_f32 v[56:57], v[10:11], v[10:11], v[58:59] op_sel_hi:[1,1,0]
	v_pk_mul_f32 v[62:63], v[42:43], v[42:43]
	v_pk_add_f32 v[54:55], v[60:61], v[54:55]
	v_pk_mul_f32 v[60:61], v[40:41], v[40:41]
	v_mov_b32_e32 v53, v64
	v_mov_b32_e32 v57, v65
	v_mov_b32_e32 v64, v33
	v_mov_b32_e32 v65, v37
	v_mov_b32_e32 v69, v39
	v_mov_b32_e32 v58, v32
	v_mov_b32_e32 v59, v36
	v_mov_b32_e32 v66, v34
	v_mov_b32_e32 v67, v38
	v_pk_mov_b32 v[74:75], v[60:61], v[62:63] op_sel:[1,0]
	v_mov_b32_e32 v61, v63
	v_pk_add_f32 v[52:53], v[52:53], v[56:57]
	v_pk_mul_f32 v[56:57], v[64:65], v[64:65]
	v_pk_mul_f32 v[62:63], v[68:69], v[68:69]
	v_pk_fma_f32 v[56:57], v[58:59], v[58:59], v[56:57]
	v_pk_fma_f32 v[58:59], v[66:67], v[66:67], v[62:63]
	v_mul_f32_e32 v71, v5, v5
	v_mul_f32_e32 v73, v6, v6
	v_mul_f32_e32 v70, v45, v45
	v_mul_f32_e32 v72, v47, v47
	v_pk_add_f32 v[60:61], v[74:75], v[60:61]
	v_pk_add_f32 v[56:57], v[56:57], v[58:59]
	v_mul_f32_e32 v31, v4, v4
	v_mul_f32_e32 v76, v7, v7
	v_pk_fma_f32 v[64:65], v[44:45], v[44:45], v[70:71] op_sel_hi:[1,1,0]
	v_pk_fma_f32 v[68:69], v[46:47], v[46:47], v[72:73] op_sel_hi:[1,1,0]
	v_pk_add_f32 v[58:59], v[60:61], v[60:61] op_sel:[0,1] op_sel_hi:[1,0]
	v_pk_add_f32 v[56:57], v[56:57], v[56:57] op_sel:[0,1] op_sel_hi:[1,0]
; __device__ __forceinline__ unsigned pk2(float lo, float hi) { f32x2_t v = {lo, hi}; bf16x2_t b = __builtin_convertvector(v, bf16x2_t); return __builtin_bit_cast(unsigned, b); }
; __device__ __forceinline__ void rms_row2048(const float* xrow, const float* g, bf16_t* orow, int lane) {
;     ...
;     for (int j = 0; j < 8; ++j) { v[j] = xr[64 * j]; s += (v[j].x * v[j].x + v[j].y * v[j].y) + (v[j].z * v[j].z + v[j].w * v[j].w); }
;     const float r = rsqrtf(wave_sum(s) * (1.f / 2048.f) + EPS);
;     u32x2* o8 = (u32x2*)orow + lane;
; #pragma unroll
;     for (int j = 0; j < 8; ++j) { const f32x4 gg = gr[64 * j]; u32x2 w; w.x = pk2(v[j].x * r * gg.x, v[j].y * r * gg.y); w.y = pk2(v[j].z * r * gg.z, v[j].w * r * gg.w); o8[64 * j] = w; }
; __global__ void __launch_bounds__(512, 2) mega_fwd(Args args) {
;     ...
;         for (int m = gw; m < T; m += NGW) rms_row2048(x + (size_t)m * D, args.in[3], H + (size_t)m * D, lane);
	v_mov_b32_e32 v65, v73
	v_mov_b32_e32 v69, v76
	v_mov_b32_e32 v59, v71
	v_mov_b32_e32 v57, v31
	v_pk_add_f32 v[60:61], v[64:65], v[68:69]
	v_pk_add_f32 v[56:57], v[56:57], v[58:59]
	v_mul_f32_e32 v77, v1, v1
	v_pk_add_f32 v[56:57], v[56:57], v[60:61]
	v_mul_f32_e32 v78, v0, v0
	v_pk_add_f32 v[54:55], v[54:55], v[54:55] op_sel:[0,1] op_sel_hi:[1,0]
	v_pk_add_f32 v[56:57], v[56:57], v[56:57] op_sel:[0,1] op_sel_hi:[1,0]
	v_mov_b32_e32 v55, v77
	v_mov_b32_e32 v57, v78
	v_pk_add_f32 v[54:55], v[56:57], v[54:55]
	s_nop 0
	v_pk_add_f32 v[52:53], v[54:55], v[52:53]
	s_nop 0
	v_add_f32_e32 v31, v52, v53
	s_nop 1
	v_add_f32_dpp v31, v31, v31 quad_perm:[1,0,3,2] row_mask:0xf bank_mask:0xf bound_ctrl:1
	s_nop 1
	v_add_f32_dpp v31, v31, v31 quad_perm:[2,3,0,1] row_mask:0xf bank_mask:0xf bound_ctrl:1
	s_nop 1
	v_add_f32_dpp v31, v31, v31 row_half_mirror row_mask:0xf bank_mask:0xf bound_ctrl:1
	s_nop 1
	v_add_f32_dpp v31, v31, v31 row_mirror row_mask:0xf bank_mask:0xf bound_ctrl:1
	s_nop 0
	v_readlane_b32 s8, v31, 16
	v_readlane_b32 s9, v31, 48
	v_readlane_b32 s6, v31, 0
	v_readlane_b32 s7, v31, 32
	v_mov_b32_e32 v52, s8
	v_mov_b32_e32 v53, s9
	v_pk_add_f32 v[52:53], s[6:7], v[52:53]
	s_nop 0
	v_add_f32_e32 v31, v52, v53
	v_fmamk_f32 v31, v31, 0x3a000000, v30
	v_mul_f32_e32 v52, 0x4b800000, v31
	v_cmp_gt_f32_e32 vcc, s4, v31
	s_nop 1
	v_cndmask_b32_e32 v31, v31, v52, vcc
	v_rsq_f32_e32 v31, v31
	s_nop 0
	v_mul_f32_e32 v52, 0x45800000, v31
	v_cndmask_b32_e32 v52, v31, v52, vcc
	v_pk_mul_f32 v[32:33], v[32:33], v[52:53] op_sel_hi:[1,0]
	v_pk_mul_f32 v[34:35], v[34:35], v[52:53] op_sel_hi:[1,0]
	v_pk_mul_f32 v[36:37], v[36:37], v[52:53] op_sel_hi:[1,0]
	v_pk_mul_f32 v[38:39], v[38:39], v[52:53] op_sel_hi:[1,0]
	v_pk_mul_f32 v[40:41], v[40:41], v[52:53] op_sel_hi:[1,0]
	v_pk_mul_f32 v[42:43], v[42:43], v[52:53] op_sel_hi:[1,0]
	v_pk_mul_f32 v[44:45], v[44:45], v[52:53] op_sel_hi:[1,0]
	v_pk_mul_f32 v[46:47], v[46:47], v[52:53] op_sel_hi:[1,0]
	v_pk_mul_f32 v[4:5], v[4:5], v[52:53] op_sel_hi:[1,0]
	v_pk_mul_f32 v[6:7], v[6:7], v[52:53] op_sel_hi:[1,0]
	v_pk_mul_f32 v[12:13], v[12:13], v[52:53] op_sel_hi:[1,0]
	v_pk_mul_f32 v[14:15], v[14:15], v[52:53] op_sel_hi:[1,0]
	v_pk_mul_f32 v[8:9], v[8:9], v[52:53] op_sel_hi:[1,0]
	v_pk_mul_f32 v[10:11], v[10:11], v[52:53] op_sel_hi:[1,0]
	v_pk_mul_f32 v[0:1], v[0:1], v[52:53] op_sel_hi:[1,0]
	v_pk_mul_f32 v[2:3], v[2:3], v[52:53] op_sel_hi:[1,0]
	v_pk_mul_f32 v[32:33], v[80:81], v[32:33]
	v_pk_mul_f32 v[34:35], v[82:83], v[34:35]
	v_pk_mul_f32 v[36:37], v[84:85], v[36:37]
	v_pk_mul_f32 v[38:39], v[86:87], v[38:39]
	v_pk_mul_f32 v[40:41], v[88:89], v[40:41]
	v_pk_mul_f32 v[42:43], v[90:91], v[42:43]
	v_pk_mul_f32 v[44:45], v[92:93], v[44:45]
	v_pk_mul_f32 v[46:47], v[94:95], v[46:47]
	v_pk_mul_f32 v[4:5], v[96:97], v[4:5]
	v_pk_mul_f32 v[6:7], v[98:99], v[6:7]
	v_pk_mul_f32 v[12:13], v[100:101], v[12:13]
	v_pk_mul_f32 v[14:15], v[102:103], v[14:15]
	v_pk_mul_f32 v[8:9], v[104:105], v[8:9]
	v_pk_mul_f32 v[10:11], v[106:107], v[10:11]
	v_pk_mul_f32 v[0:1], v[108:109], v[0:1]
	v_pk_mul_f32 v[2:3], v[110:111], v[2:3]
	v_cvt_pk_bf16_f32 v32, v32, v33
	v_cvt_pk_bf16_f32 v33, v34, v35
	v_cvt_pk_bf16_f32 v36, v36, v37
	v_cvt_pk_bf16_f32 v37, v38, v39
	v_cvt_pk_bf16_f32 v40, v40, v41
	v_cvt_pk_bf16_f32 v41, v42, v43
	v_cvt_pk_bf16_f32 v44, v44, v45
	v_cvt_pk_bf16_f32 v45, v46, v47
	v_cvt_pk_bf16_f32 v4, v4, v5
	v_cvt_pk_bf16_f32 v5, v6, v7
	v_cvt_pk_bf16_f32 v12, v12, v13
	v_cvt_pk_bf16_f32 v13, v14, v15
	v_cvt_pk_bf16_f32 v8, v8, v9
	v_cvt_pk_bf16_f32 v9, v10, v11
	v_cvt_pk_bf16_f32 v0, v0, v1
	v_cvt_pk_bf16_f32 v1, v2, v3
	global_store_dwordx2 v[26:27], v[32:33], off offset:-3584
	global_store_dwordx2 v[26:27], v[36:37], off offset:-3072
	global_store_dwordx2 v[26:27], v[40:41], off offset:-2560
	global_store_dwordx2 v[26:27], v[44:45], off offset:-2048
	global_store_dwordx2 v[26:27], v[4:5], off offset:-1536
	global_store_dwordx2 v[26:27], v[12:13], off offset:-1024
	global_store_dwordx2 v[26:27], v[8:9], off offset:-512
	global_store_dwordx2 v[26:27], v[0:1], off
	v_lshl_add_u64 v[26:27], v[26:27], 0, s[0:1]
	s_cmp_lg_u32 s17, 0
	s_cbranch_scc0 .Lp0r_done
	s_waitcnt vmcnt(8)
	s_branch .LBB0_259
.Lp0r_done:
.LBB0_260:
	s_cmp_gt_i32 s93, 1
	s_cselect_b64 s[12:13], -1, 0
	s_and_b64 s[0:1], s[10:11], s[12:13]
	s_andn2_b64 vcc, exec, s[0:1]
	s_cbranch_vccnz .LBB0_314
	s_waitcnt vmcnt(0)
	s_waitcnt lgkmcnt(0)
	s_barrier
	s_mov_b64 s[0:1], exec
	v_readlane_b32 s2, v238, 3
	v_readlane_b32 s3, v238, 4
	s_and_b64 s[2:3], s[0:1], s[2:3]
	s_mov_b64 exec, s[2:3]
	s_cbranch_execz .LBB0_313
	s_add_i32 s2, 0, 0x20600
	v_mov_b32_e32 v0, s2
	s_waitcnt vmcnt(0) expcnt(0) lgkmcnt(0)
	ds_read_b32 v2, v0
	s_add_i32 s2, 0, 0x20604
	v_mov_b32_e32 v0, s2
	ds_read_b32 v0, v0
	s_waitcnt lgkmcnt(1)
	v_cmp_ne_u32_e32 vcc, 0, v2
	s_cbranch_vccnz .LBB0_277
	v_readlane_b32 s2, v238, 0
	v_readlane_b32 s3, v238, 1
	s_load_dwordx2 s[6:7], s[2:3], 0x4
	s_add_u32 s2, s86, 0x6700200
	s_addc_u32 s3, s87, 0
	s_add_u32 s4, s86, 0x6700400
	s_addc_u32 s5, s87, 0
	s_waitcnt lgkmcnt(0)
	s_mul_i32 s14, s6, s15
	s_add_u32 s6, s86, 0x6700500
	s_mul_i32 s14, s14, s7
	s_addc_u32 s7, s87, 0
	s_add_u32 s8, s86, 0x6700600
	s_addc_u32 s9, s87, 0
	s_add_u32 s10, s86, 0x6700700
	s_addc_u32 s11, s87, 0
	s_add_u32 s16, s86, 0x6700800
	s_addc_u32 s17, s87, 0
	s_add_u32 s40, s86, 0x6700900
	s_addc_u32 s41, s87, 0
	s_add_u32 s42, s86, 0x6700a00
	s_addc_u32 s43, s87, 0
	s_add_u32 s46, s86, 0x6700b00
	s_addc_u32 s47, s87, 0
	s_add_u32 s48, s86, 0x6700c00
	s_addc_u32 s49, s87, 0
	s_add_u32 s50, s86, 0x6700d00
	s_addc_u32 s51, s87, 0
	s_add_u32 s58, s86, 0x6700e00
	s_addc_u32 s59, s87, 0
	s_add_u32 s60, s86, 0x6700f00
	s_addc_u32 s61, s87, 0
	s_add_u32 s62, s86, 0x6701000
	s_addc_u32 s63, s87, 0
	s_add_u32 s64, s86, 0x6701100
	s_addc_u32 s65, s87, 0
	s_add_u32 s66, s86, 0x6701200
	s_addc_u32 s67, s87, 0
	s_add_u32 s68, s86, 0x6701300
	s_addc_u32 s69, s87, 0
	s_mov_b32 s33, 1
	v_mov_b32_e32 v16, 0
	s_branch .LBB0_265
